# attention loop: running-max offset folded into the QK MFMA accumulator init (f32), 32 subs + flag test per tile removed
# speedup vs baseline: 1.0010x; 1.0010x over previous
.Lq1_body:
	global_load_dwordx4 v[28:31], v202, s[100:101] offset:-128
	global_load_dwordx4 v[32:35], v202, s[100:101]
	global_load_dwordx4 v[4:7], v203, s[100:101] offset:-128
	global_load_dwordx4 v[12:15], v203, s[100:101]
	ds_read_b128 v[44:47], v214 offset:35840
	ds_read_b128 v[72:75], v214 offset:35904
	ds_read_b128 v[92:95], v214 offset:40192
	ds_read_b128 v[112:115], v214 offset:40256
	v_xor_b32_e32 v222, 0x80000000, v196
	v_xor_b32_e32 v223, 0x80000000, v196
	v_xor_b32_e32 v224, 0x80000000, v196
	v_xor_b32_e32 v225, 0x80000000, v196
	v_xor_b32_e32 v226, 0x80000000, v197
	v_xor_b32_e32 v227, 0x80000000, v197
	v_xor_b32_e32 v228, 0x80000000, v197
	v_xor_b32_e32 v229, 0x80000000, v197
	ds_read_b128 v[132:135], v214 offset:44544
	ds_read_b128 v[148:151], v214 offset:44608
	ds_read_b128 v[136:139], v214 offset:48896
	ds_read_b128 v[152:155], v214 offset:48960
	s_waitcnt lgkmcnt(7)
	v_mfma_f32_16x16x32_bf16 v[140:143], v[44:47], v[8:11], v[222:225]
	v_mfma_f32_16x16x32_bf16 v[44:47], v[44:47], v[20:23], v[226:229]
	s_waitcnt lgkmcnt(1)
	v_mfma_f32_16x16x32_bf16 v[156:159], v[92:95], v[8:11], v[222:225]
	v_mfma_f32_16x16x32_bf16 v[92:95], v[92:95], v[20:23], v[226:229]
	v_mfma_f32_16x16x32_bf16 v[160:163], v[132:135], v[8:11], v[222:225]
	v_mfma_f32_16x16x32_bf16 v[132:135], v[132:135], v[20:23], v[226:229]
	v_mfma_f32_16x16x32_bf16 v[164:167], v[136:139], v[8:11], v[222:225]
	v_mfma_f32_16x16x32_bf16 v[168:171], v[136:139], v[20:23], v[226:229]
	v_mfma_f32_16x16x32_bf16 v[144:147], v[72:75], v[16:19], v[140:143]
	v_mfma_f32_16x16x32_bf16 v[136:139], v[72:75], v[24:27], v[44:47]
	v_mfma_f32_16x16x32_bf16 v[44:47], v[112:115], v[16:19], v[156:159]
	v_mfma_f32_16x16x32_bf16 v[92:95], v[112:115], v[24:27], v[92:95]
	v_mfma_f32_16x16x32_bf16 v[140:143], v[148:151], v[16:19], v[160:163]
	v_mfma_f32_16x16x32_bf16 v[132:135], v[148:151], v[24:27], v[132:135]
	s_waitcnt lgkmcnt(0)
	v_mfma_f32_16x16x32_bf16 v[72:75], v[152:155], v[16:19], v[164:167]
	v_mfma_f32_16x16x32_bf16 v[112:115], v[152:155], v[24:27], v[168:171]

.Lq1_h2_nok:
	global_load_dwordx4 v[4:7], v203, s[100:101] offset:-128
	global_load_dwordx4 v[12:15], v203, s[100:101]
	s_cmp_ge_u32 s89, s83
	s_cbranch_scc1 .Lq1_h2_pvonly
	ds_read_b128 v[36:39], v214
	ds_read_b128 v[40:43], v214 offset:64
	ds_read_b128 v[60:63], v214 offset:4352
	ds_read_b128 v[84:87], v214 offset:4416
	v_xor_b32_e32 v222, 0x80000000, v196
	v_xor_b32_e32 v223, 0x80000000, v196
	v_xor_b32_e32 v224, 0x80000000, v196
	v_xor_b32_e32 v225, 0x80000000, v196
	v_xor_b32_e32 v226, 0x80000000, v197
	v_xor_b32_e32 v227, 0x80000000, v197
	v_xor_b32_e32 v228, 0x80000000, v197
	v_xor_b32_e32 v229, 0x80000000, v197
	ds_read_b128 v[64:67], v214 offset:8704
	ds_read_b128 v[124:127], v214 offset:8768
	ds_read_b128 v[108:111], v214 offset:13056
	ds_read_b128 v[100:103], v214 offset:13120
	s_waitcnt lgkmcnt(7)
	v_mfma_f32_16x16x32_bf16 v[120:123], v[36:39], v[8:11], v[222:225]
	v_mfma_f32_16x16x32_bf16 v[36:39], v[36:39], v[20:23], v[226:229]
	s_waitcnt lgkmcnt(1)
	v_mfma_f32_16x16x32_bf16 v[116:119], v[60:63], v[8:11], v[222:225]
	v_mfma_f32_16x16x32_bf16 v[60:63], v[60:63], v[20:23], v[226:229]
	v_mfma_f32_16x16x32_bf16 v[96:99], v[64:67], v[8:11], v[222:225]
	v_mfma_f32_16x16x32_bf16 v[64:67], v[64:67], v[20:23], v[226:229]
	v_mfma_f32_16x16x32_bf16 v[104:107], v[108:111], v[8:11], v[222:225]
	v_mfma_f32_16x16x32_bf16 v[76:79], v[108:111], v[20:23], v[226:229]
	v_mfma_f32_16x16x32_bf16 v[128:131], v[40:43], v[16:19], v[120:123]
	v_mfma_f32_16x16x32_bf16 v[108:111], v[40:43], v[24:27], v[36:39]
	v_mfma_f32_16x16x32_bf16 v[36:39], v[84:87], v[16:19], v[116:119]
	v_mfma_f32_16x16x32_bf16 v[60:63], v[84:87], v[24:27], v[60:63]
	v_mfma_f32_16x16x32_bf16 v[120:123], v[124:127], v[16:19], v[96:99]
	v_mfma_f32_16x16x32_bf16 v[64:67], v[124:127], v[24:27], v[64:67]
	s_waitcnt lgkmcnt(0)
	v_mfma_f32_16x16x32_bf16 v[40:43], v[100:103], v[16:19], v[104:107]
	v_mfma_f32_16x16x32_bf16 v[84:87], v[100:103], v[24:27], v[76:79]
